# NSA item: agent-scope loads of compressed K/V instead of a per-item L2 invalidate
# baseline (speedup 1.0000x reference)
; DEVI int opaque_tid(int wv) { int t; asm volatile("v_mbcnt_lo_u32_b32 %0, -1, 0\n\tv_mbcnt_hi_u32_b32 %0, -1, %0" : "=v"(t)); return wv * 64 + t; }
; DEVI void nsa_item(const Ctx& cx, const unsigned* cflag, int b, int g, int qt, unsigned char* lds, int wv) {
;     ...
;   if (lane0 < 64) {
;     if (lane0 == 0) { while (__hip_atomic_load(cflag + b, __ATOMIC_RELAXED, __HIP_MEMORY_SCOPE_AGENT) < 2u) __builtin_amdgcn_s_sleep(2); }
;     __builtin_amdgcn_fence(__ATOMIC_ACQUIRE, "agent");
;     asm volatile("s_waitcnt vmcnt(0)" ::: "memory");
;   }
;   __syncthreads();
;   }
;   const int tid = opaque_tid(wv), lane = tid & 63, wave = tid >> 6, idx = lane & 15, quad = lane >> 4;
;   const int t0 = qt * 128;
;   const int tq = t0 + wave * 16 + idx;
;   const unsigned tokrow = (unsigned)(b * S + tq);
;   const bf16_t* proj = cx.proj;
;   const int lc = tid & 7, lr = tid >> 3;
;   f32x4* const scrb = (f32x4*)cx.xb; const unsigned scro = ((unsigned)(blockIdx.x * 8 + wave) * 64u + (unsigned)lane) * 12u;
;     ...
;   bf16x8 q[3][2];
; #pragma unroll
;   for (int c = 0; c < 3; ++c)
; #pragma unroll
;     for (int ks = 0; ks < 2; ++ks) q[c][ks] = *(const bf16x8*)(proj + (size_t)tokrow * PS + C_Q + (g * 3 + c) * 64 + ks * 32 + quad * 8);
;   f32x4 o[3][4];
;   float mr[3], lrn[3];
; #pragma unroll
;   for (int c = 0; c < 3; ++c) {
;     mr[c] = -1e30f; lrn[c] = 0.f;
; #pragma unroll
;     for (int d = 0; d < 4; ++d) o[c][d] = (f32x4){0.f, 0.f, 0.f, 0.f};
;   }
;   float* impA = (float*)(lds + ATT_IMPA); float* impB = (float*)(lds + ATT_IMPB);
;   unsigned* selm = (unsigned*)(lds + ATT_SELM); unsigned* bmaskp = (unsigned*)(lds + ATT_BMASK);
; #pragma unroll
;   for (int kt64 = 0; kt64 < 2; ++kt64) {
;     u32x4 kr = *(const u32x4*)(cx.kc + ((size_t)((b * 128 + kt64 * 64 + lr) * 2 + g)) * 64 + lc * 8);
;     u32x4 vr = *(const u32x4*)(cx.vcT + ((size_t)((b * 2 + g) * 64 + lr)) * 128 + kt64 * 64 + lc * 8);
;     *(u32x4*)(lds + ATT_K0 + kt64 * ATT_KSZ + lr * LDS_ROW + lc * 16) = kr;
;     *(u32x4*)(lds + ATT_V0 + kt64 * ATT_VSZ + lr * LDS_ROW + lc * 16) = vr;
;   }
;   if (tid == 0) *bmaskp = 0u;
.LBB0_1400:
	s_or_b64 exec, exec, s[4:5]
	s_waitcnt vmcnt(0)
	s_waitcnt vmcnt(0)
.LBB0_1401:
	s_or_b64 exec, exec, s[0:1]
	s_and_b32 s21, s8, 1
	s_cmpk_lt_i32 s3, 0x70
	s_cselect_b32 s0, 15, 14
	v_readlane_b32 s1, v255, 19
	s_sub_i32 s3, s0, s1
	v_readlane_b32 s0, v252, 46
	s_barrier
	v_mbcnt_lo_u32_b32 v116, -1, 0
	v_mbcnt_hi_u32_b32 v116, -1, v116
	s_lshl_b32 s20, s3, 7
	v_add_u32_e32 v119, s0, v116
	v_ashrrev_i32_e32 v114, 2, v119
	s_waitcnt vmcnt(8)
	v_and_b32_e32 v28, -16, v114
	v_and_b32_e32 v25, 15, v116
	v_add_u32_e32 v124, s20, v28
	v_readlane_b32 s4, v252, 40
	v_or_b32_e32 v125, v124, v25
	s_lshl_b32 s97, s2, 11
	v_readlane_b32 s6, v252, 42
	v_readlane_b32 s7, v252, 43
	v_add_u32_e32 v123, s97, v125
	v_ashrrev_i32_e32 v112, 3, v119
	v_mov_b64_e32 v[0:1], s[6:7]
	v_mad_u64_u32 v[0:1], s[0:1], v123, s33, v[0:1]
	s_lshl_b32 s0, s2, 7
	s_lshl_b32 s2, s21, 6
	v_add_u32_e32 v24, s0, v112
	s_or_b32 s0, s0, s2
	v_add_u32_e32 v94, s0, v112
	s_movk_i32 s0, 0x90
	v_lshl_or_b32 v44, v24, 1, s21
	v_readlane_b32 s5, v252, 41
	v_mul_lo_u32 v27, v112, s0
	v_ashrrev_i32_e32 v45, 31, v44
	v_readlane_b32 s0, v253, 36
	v_and_b32_e32 v26, 7, v116
	v_and_b32_e32 v32, 48, v116
	s_mul_i32 s96, s21, 0xc0
	v_ashrrev_i32_e32 v95, 31, v94
	v_lshlrev_b64 v[34:35], 7, v[44:45]
	v_readlane_b32 s1, v253, 37
	v_readlane_b32 s4, v253, 38
	v_lshl_add_u64 v[0:1], v[0:1], 0, v[32:33]
	s_lshl_b32 s92, s96, 1
	v_lshlrev_b64 v[30:31], 8, v[94:95]
	v_lshlrev_b32_e32 v42, 4, v26
	v_lshl_add_u64 v[34:35], s[0:1], 0, v[34:35]
	v_mov_b32_e32 v43, v33
	v_readlane_b32 s5, v253, 39
	v_lshl_add_u64 v[92:93], v[0:1], 0, s[92:93]
	v_lshl_add_u64 v[34:35], v[34:35], 0, v[42:43]
	v_lshl_add_u64 v[30:31], s[4:5], 0, v[30:31]
	global_load_dwordx4 v[0:3], v[92:93], off
	global_load_dwordx4 v[4:7], v[92:93], off offset:64
	global_load_dwordx4 v[8:11], v[92:93], off offset:128
	global_load_dwordx4 v[12:15], v[92:93], off offset:192
	global_load_dwordx4 v[16:19], v[92:93], off offset:256
	global_load_dwordx4 v[20:23], v[92:93], off offset:320
	v_lshl_add_u64 v[30:31], v[30:31], 0, v[42:43]
	global_load_dwordx4 v[34:37], v[34:35], off sc1
	v_add3_u32 v126, 0, v27, v42
	global_load_dwordx4 v[38:41], v[30:31], off sc1
	v_cmp_eq_u32_e32 vcc, 0, v119
	s_waitcnt vmcnt(1)
	ds_write_b128 v126, v[34:37]
	s_waitcnt vmcnt(0)
	ds_write_b128 v126, v[38:41] offset:26624
	v_add_u32_e32 v34, 0x80, v44
	v_ashrrev_i32_e32 v35, 31, v34
	v_lshlrev_b64 v[34:35], 7, v[34:35]
	v_lshl_add_u64 v[34:35], s[0:1], 0, v[34:35]
	v_lshl_add_u64 v[34:35], v[34:35], 0, v[42:43]
	global_load_dwordx4 v[34:37], v[34:35], off sc1
	s_nop 0
	global_load_dwordx4 v[38:41], v[30:31], off offset:128 sc1
	s_waitcnt vmcnt(1)
	ds_write_b128 v126, v[34:37] offset:13312
	s_waitcnt vmcnt(0)
	ds_write_b128 v126, v[38:41] offset:35840
	s_and_saveexec_b64 s[0:1], vcc
	s_cbranch_execz .LBB0_1403
	v_readlane_b32 s4, v254, 51
	s_nop 1
	v_mov_b32_e32 v24, s4
	ds_write_b32 v24, v33
